# S5 jobs: remaining token groups touched once at job start so pass-1 operand loads hit L2
# baseline (speedup 1.0000x reference)
.LBB0_281:
	s_or_b64 exec, exec, s[18:19]
	v_mov_b32_e32 v0, s2
	s_waitcnt lgkmcnt(0)
	s_barrier
	ds_read_b32 v0, v0
	s_movk_i32 s0, 0x1ff
	s_mov_b64 s[18:19], -1
	s_waitcnt lgkmcnt(0)
	v_cmp_lt_i32_e32 vcc, s0, v0
	v_readfirstlane_b32 s21, v0
	s_cbranch_vccnz .LBB0_276
	s_and_b32 s20, s21, 31
	s_or_b32 s0, s20, s4
	s_ashr_i32 s1, s0, 31
	s_lshl_b64 s[0:1], s[0:1], 2
	s_add_u32 s0, s40, s0
	s_addc_u32 s1, s41, s1
	global_load_dword v0, v199, s[0:1]
	s_lshl_b32 s52, s20, 6
	s_or_b32 s18, s14, s52
	s_mov_b32 s19, s15
	s_lshl_b32 s0, s20, 10
	s_or_b32 s0, s16, s0
	s_mov_b32 s1, s17
	s_lshl_b64 s[0:1], s[0:1], 2
	v_mov_b32_e32 v76, 0
	s_lshl_b32 s22, s20, 4
	s_waitcnt vmcnt(0)
	v_mul_f32_e32 v1, 0x3fb8aa3b, v0
	v_fma_f32 v2, v0, s92, -v1
	v_rndne_f32_e32 v3, v1
	v_fmac_f32_e32 v2, 0x32a5705f, v0
	v_sub_f32_e32 v1, v1, v3
	v_add_f32_e32 v1, v1, v2
	v_exp_f32_e32 v1, v1
	v_cvt_i32_f32_e32 v2, v3
	v_cmp_ngt_f32_e32 vcc, s65, v0
	v_ldexp_f32 v1, v1, v2
	s_nop 0
	v_cndmask_b32_e32 v1, 0, v1, vcc
	v_cmp_nlt_f32_e32 vcc, s56, v0
	v_or_b32_e32 v0, s18, v44
	s_nop 0
	v_cndmask_b32_e32 v30, v246, v1, vcc
	v_mov_b32_e32 v1, s15
	v_lshlrev_b64 v[0:1], 2, v[0:1]
	v_lshl_add_u64 v[2:3], s[36:37], 0, v[0:1]
	v_lshl_add_u64 v[0:1], s[38:39], 0, v[0:1]
	global_load_dword v0, v[0:1], off
	s_waitcnt vmcnt(0)
	v_mul_f32_e32 v0, v30, v0
	global_load_dword v2, v[2:3], off
	v_mul_f32_e32 v1, 0.15915494, v0
	v_rndne_f32_e32 v1, v1
	v_fmac_f32_e32 v0, 0xc0c90fdb, v1
	v_fmac_f32_e32 v0, 0x343bbd2e, v1
	v_mul_f32_e32 v41, 0.15915494, v0
	v_cos_f32_e32 v40, v41
	v_sin_f32_e32 v41, v41
	s_waitcnt vmcnt(0)
	v_mul_f32_e32 v0, v30, v2
	v_mul_f32_e32 v1, 0x3fb8aa3b, v0
	v_fma_f32 v2, v0, s92, -v1
	v_rndne_f32_e32 v3, v1
	v_fmac_f32_e32 v2, 0x32a5705f, v0
	v_sub_f32_e32 v1, v1, v3
	v_add_f32_e32 v1, v1, v2
	v_exp_f32_e32 v1, v1
	v_cvt_i32_f32_e32 v2, v3
	v_cmp_ngt_f32_e32 vcc, s65, v0
	v_ldexp_f32 v1, v1, v2
	s_nop 0
	v_cndmask_b32_e32 v1, 0, v1, vcc
	v_cmp_nlt_f32_e32 vcc, s56, v0
	v_or_b32_e32 v0, s18, v46
	s_nop 0
	v_cndmask_b32_e32 v42, v246, v1, vcc
	v_mov_b32_e32 v1, s15
	v_lshlrev_b64 v[2:3], 2, v[0:1]
	v_lshl_add_u64 v[4:5], s[36:37], 0, v[2:3]
	v_lshl_add_u64 v[2:3], s[38:39], 0, v[2:3]
	global_load_dword v4, v[4:5], off
	v_lshlrev_b64 v[0:1], 6, v[0:1]
	global_load_dword v5, v[2:3], off
	v_lshl_add_u64 v[12:13], v[50:51], 0, v[0:1]
	s_waitcnt vmcnt(0)
	v_mul_f32_e32 v2, v30, v5
	v_mul_f32_e32 v3, 0.15915494, v2
	v_rndne_f32_e32 v3, v3
	v_fmac_f32_e32 v2, 0xc0c90fdb, v3
	v_fmac_f32_e32 v2, 0x343bbd2e, v3
	v_mul_f32_e32 v2, 0.15915494, v2
	v_sin_f32_e32 v3, v2
	v_cos_f32_e32 v8, v2
	v_mul_f32_e32 v2, v30, v4
	v_mul_f32_e32 v6, 0x3fb8aa3b, v2
	v_fma_f32 v7, v2, s92, -v6
	v_rndne_f32_e32 v9, v6
	v_fmac_f32_e32 v7, 0x32a5705f, v2
	v_sub_f32_e32 v6, v6, v9
	v_add_f32_e32 v6, v6, v7
	v_exp_f32_e32 v6, v6
	v_cvt_i32_f32_e32 v7, v9
	v_cmp_ngt_f32_e32 vcc, s65, v2
	v_ldexp_f32 v6, v6, v7
	s_nop 0
	v_cndmask_b32_e32 v6, 0, v6, vcc
	v_cmp_nlt_f32_e32 vcc, s56, v2
	s_nop 1
	v_cndmask_b32_e32 v9, v246, v6, vcc
	v_pk_mul_f32 v[6:7], v[4:5], v[4:5]
	v_mul_f32_e32 v2, v9, v3
	v_add_f32_e32 v3, v6, v7
	v_rcp_f32_e32 v10, v3
	v_fma_f32 v3, v9, v8, -1.0
	v_mov_b32_e32 v6, v5
	v_mov_b32_e32 v7, v4
	v_pk_mul_f32 v[6:7], v[6:7], v[2:3]
	v_pk_mul_f32 v[2:3], v[4:5], v[2:3]
	v_add_f32_e32 v6, v6, v7
	v_sub_f32_e32 v2, v2, v3
	v_lshl_add_u64 v[4:5], v[48:49], 0, v[0:1]
	v_mul_f32_e32 v16, v10, v6
	v_mul_f32_e32 v18, v10, v2
	global_load_dwordx4 v[0:3], v[4:5], off offset:16
	s_nop 0
	global_load_dwordx4 v[4:7], v[4:5], off
	s_nop 0
	global_load_dwordx4 v[8:11], v[12:13], off offset:16
	s_nop 0
	global_load_dwordx4 v[12:15], v[12:13], off
	s_waitcnt vmcnt(0)
	v_pk_mul_f32 v[20:21], v[12:13], v[16:17] op_sel_hi:[1,0]
	v_pk_mul_f32 v[12:13], v[12:13], v[18:19] op_sel_hi:[1,0]
	v_pk_fma_f32 v[20:21], v[4:5], v[18:19], v[20:21] op_sel_hi:[1,0,1]
	v_pk_fma_f32 v[4:5], v[4:5], v[16:17], v[12:13] op_sel_hi:[1,0,1] neg_lo:[0,0,1] neg_hi:[0,0,1]
	s_nop 0
	v_cvt_pk_bf16_f32 v17, v4, v20
	v_cvt_pk_bf16_f32 v19, v5, v21
	v_lshlrev_b32_e32 v13, 16, v19
	v_lshlrev_b32_e32 v12, 16, v17
	v_pk_add_f32 v[12:13], v[4:5], v[12:13] neg_lo:[0,1] neg_hi:[0,1]
	s_nop 0
	v_cndmask_b32_e64 v22, v5, v13, s[8:9]
	v_cndmask_b32_e64 v23, v4, v12, s[8:9]
	v_and_b32_e32 v5, 0xffff0000, v19
	v_and_b32_e32 v4, 0xffff0000, v17
	v_pk_add_f32 v[4:5], v[20:21], v[4:5] neg_lo:[0,1] neg_hi:[0,1]
	s_nop 0
	v_cndmask_b32_e64 v17, v21, v5, s[8:9]
	v_cndmask_b32_e64 v19, v20, v4, s[8:9]
	v_pk_mul_f32 v[4:5], v[14:15], v[16:17] op_sel_hi:[1,0]
	v_pk_mul_f32 v[12:13], v[14:15], v[18:19] op_sel_hi:[1,0]
	v_pk_fma_f32 v[4:5], v[6:7], v[18:19], v[4:5] op_sel_hi:[1,0,1]
	v_pk_fma_f32 v[6:7], v[6:7], v[16:17], v[12:13] op_sel_hi:[1,0,1] neg_lo:[0,0,1] neg_hi:[0,0,1]
	s_nop 0
	v_cvt_pk_bf16_f32 v14, v6, v4
	v_cvt_pk_bf16_f32 v15, v7, v5
	v_lshlrev_b32_e32 v13, 16, v15
	v_lshlrev_b32_e32 v12, 16, v14
	v_pk_add_f32 v[12:13], v[6:7], v[12:13] neg_lo:[0,1] neg_hi:[0,1]
	s_nop 0
	v_cndmask_b32_e64 v13, v7, v13, s[8:9]
	v_cndmask_b32_e64 v12, v6, v12, s[8:9]
	v_and_b32_e32 v7, 0xffff0000, v15
	v_and_b32_e32 v6, 0xffff0000, v14
	v_pk_add_f32 v[6:7], v[4:5], v[6:7] neg_lo:[0,1] neg_hi:[0,1]
	s_nop 0
	v_cndmask_b32_e64 v14, v5, v7, s[8:9]
	v_cndmask_b32_e64 v15, v4, v6, s[8:9]
	v_pk_mul_f32 v[4:5], v[8:9], v[16:17] op_sel_hi:[1,0]
	v_pk_mul_f32 v[6:7], v[8:9], v[18:19] op_sel_hi:[1,0]
	v_pk_fma_f32 v[4:5], v[0:1], v[18:19], v[4:5] op_sel_hi:[1,0,1]
	v_pk_fma_f32 v[0:1], v[0:1], v[16:17], v[6:7] op_sel_hi:[1,0,1] neg_lo:[0,0,1] neg_hi:[0,0,1]
	s_nop 0
	v_cvt_pk_bf16_f32 v8, v0, v4
	v_cvt_pk_bf16_f32 v9, v1, v5
	v_lshlrev_b32_e32 v7, 16, v9
	v_lshlrev_b32_e32 v6, 16, v8
	v_pk_add_f32 v[6:7], v[0:1], v[6:7] neg_lo:[0,1] neg_hi:[0,1]
	s_nop 0
	v_cndmask_b32_e64 v7, v1, v7, s[8:9]
	v_cndmask_b32_e64 v6, v0, v6, s[8:9]
	v_and_b32_e32 v1, 0xffff0000, v9
	v_and_b32_e32 v0, 0xffff0000, v8
	v_pk_add_f32 v[0:1], v[4:5], v[0:1] neg_lo:[0,1] neg_hi:[0,1]
	s_nop 0
	v_cndmask_b32_e64 v8, v5, v1, s[8:9]
	v_cndmask_b32_e64 v9, v4, v0, s[8:9]
	v_pk_mul_f32 v[0:1], v[16:17], v[10:11] op_sel_hi:[0,1]
	v_pk_mul_f32 v[4:5], v[18:19], v[10:11] op_sel_hi:[0,1]
	v_pk_fma_f32 v[0:1], v[18:19], v[2:3], v[0:1] op_sel_hi:[0,1,1]
	v_pk_fma_f32 v[2:3], v[16:17], v[2:3], v[4:5] op_sel_hi:[0,1,1] neg_lo:[0,0,1] neg_hi:[0,0,1]
	v_cvt_pk_bf16_f32 v10, v2, v0
	v_cvt_pk_bf16_f32 v11, v3, v1
	v_lshlrev_b32_e32 v5, 16, v11
	v_lshlrev_b32_e32 v4, 16, v10
	v_pk_add_f32 v[4:5], v[2:3], v[4:5] neg_lo:[0,1] neg_hi:[0,1]
	s_nop 0
	v_cndmask_b32_e64 v5, v3, v5, s[8:9]
	v_cndmask_b32_e64 v4, v2, v4, s[8:9]
	v_and_b32_e32 v3, 0xffff0000, v11
	v_and_b32_e32 v2, 0xffff0000, v10
	v_pk_add_f32 v[2:3], v[0:1], v[2:3] neg_lo:[0,1] neg_hi:[0,1]
	s_nop 0
	v_cndmask_b32_e64 v10, v1, v3, s[8:9]
	v_cndmask_b32_e64 v11, v0, v2, s[8:9]
	v_cvt_pk_bf16_f32 v2, v6, v7
	v_cvt_pk_bf16_f32 v7, v11, v10
	v_lshl_add_u64 v[10:11], s[18:19], 0, v[46:47]
	v_lshlrev_b64 v[10:11], 2, v[10:11]
	v_lshl_add_u64 v[24:25], s[38:39], 0, v[10:11]
	v_cvt_pk_bf16_f32 v1, v12, v13
	global_load_dword v13, v[24:25], off offset:64
	v_lshl_add_u64 v[28:29], s[36:37], 0, v[10:11]
	global_load_dword v12, v[28:29], off offset:64
	v_cvt_pk_bf16_f32 v3, v4, v5
	v_cvt_pk_bf16_f32 v5, v15, v14
	v_cvt_pk_bf16_f32 v4, v19, v17
	v_cvt_pk_bf16_f32 v6, v9, v8
	v_mov_b32_e32 v9, s15
	v_or_b32_e32 v8, s18, v62
	v_lshlrev_b64 v[8:9], 6, v[8:9]
	v_lshl_add_u64 v[18:19], v[48:49], 0, v[8:9]
	v_lshl_add_u64 v[8:9], v[50:51], 0, v[8:9]
	v_cvt_pk_bf16_f32 v0, v23, v22
	s_waitcnt vmcnt(1)
	v_mul_f32_e32 v10, v30, v13
	v_mul_f32_e32 v11, 0.15915494, v10
	v_rndne_f32_e32 v11, v11
	v_fmac_f32_e32 v10, 0xc0c90fdb, v11
	v_fmac_f32_e32 v10, 0x343bbd2e, v11
	v_mul_f32_e32 v10, 0.15915494, v10
	v_sin_f32_e32 v11, v10
	v_cos_f32_e32 v15, v10
	s_waitcnt vmcnt(0)
	v_mul_f32_e32 v10, v30, v12
	v_mul_f32_e32 v14, 0x3fb8aa3b, v10
	v_fma_f32 v16, v10, s92, -v14
	v_rndne_f32_e32 v17, v14
	v_fmac_f32_e32 v16, 0x32a5705f, v10
	v_sub_f32_e32 v14, v14, v17
	v_add_f32_e32 v14, v14, v16
	v_exp_f32_e32 v14, v14
	v_cvt_i32_f32_e32 v16, v17
	v_cmp_ngt_f32_e32 vcc, s65, v10
	v_ldexp_f32 v14, v14, v16
	s_nop 0
	v_cndmask_b32_e32 v14, 0, v14, vcc
	v_cmp_nlt_f32_e32 vcc, s56, v10
	s_nop 1
	v_cndmask_b32_e32 v16, v246, v14, vcc
	v_mul_f32_e32 v14, v16, v11
	v_pk_mul_f32 v[10:11], v[12:13], v[12:13]
	v_fma_f32 v15, v16, v15, -1.0
	v_add_f32_e32 v10, v10, v11
	v_rcp_f32_e32 v17, v10
	v_mov_b32_e32 v10, v13
	v_mov_b32_e32 v11, v12
	v_pk_mul_f32 v[10:11], v[10:11], v[14:15]
	v_pk_mul_f32 v[12:13], v[12:13], v[14:15]
	v_add_f32_e32 v10, v10, v11
	v_sub_f32_e32 v11, v12, v13
	v_mul_f32_e32 v10, v17, v10
	v_mul_f32_e32 v12, v17, v11
	global_load_dwordx4 v[14:17], v[18:19], off offset:16
	s_nop 0
	global_load_dwordx4 v[18:21], v[18:19], off
	s_nop 0
	global_load_dwordx4 v[32:35], v[8:9], off offset:16
	global_load_dwordx4 v[36:39], v[8:9], off
	s_waitcnt vmcnt(0)
	v_pk_mul_f32 v[8:9], v[36:37], v[10:11] op_sel_hi:[1,0]
	v_pk_mul_f32 v[22:23], v[36:37], v[12:13] op_sel_hi:[1,0]
	v_pk_fma_f32 v[8:9], v[18:19], v[12:13], v[8:9] op_sel_hi:[1,0,1]
	v_pk_fma_f32 v[18:19], v[18:19], v[10:11], v[22:23] op_sel_hi:[1,0,1] neg_lo:[0,0,1] neg_hi:[0,0,1]
	s_nop 0
	v_cvt_pk_bf16_f32 v11, v18, v8
	v_cvt_pk_bf16_f32 v13, v19, v9
	v_lshlrev_b32_e32 v23, 16, v13
	v_lshlrev_b32_e32 v22, 16, v11
	v_pk_add_f32 v[22:23], v[18:19], v[22:23] neg_lo:[0,1] neg_hi:[0,1]
	s_nop 0
	v_cndmask_b32_e64 v23, v19, v23, s[8:9]
	v_cndmask_b32_e64 v22, v18, v22, s[8:9]
	v_and_b32_e32 v19, 0xffff0000, v13
	v_and_b32_e32 v18, 0xffff0000, v11
	v_pk_add_f32 v[18:19], v[8:9], v[18:19] neg_lo:[0,1] neg_hi:[0,1]
	s_nop 0
	v_cndmask_b32_e64 v26, v9, v19, s[8:9]
	v_cndmask_b32_e64 v27, v8, v18, s[8:9]
	v_pk_mul_f32 v[8:9], v[38:39], v[10:11] op_sel_hi:[1,0]
	v_pk_mul_f32 v[18:19], v[38:39], v[12:13] op_sel_hi:[1,0]
	v_pk_fma_f32 v[8:9], v[20:21], v[12:13], v[8:9] op_sel_hi:[1,0,1]
	v_pk_fma_f32 v[18:19], v[20:21], v[10:11], v[18:19] op_sel_hi:[1,0,1] neg_lo:[0,0,1] neg_hi:[0,0,1]
	s_nop 0
	v_cvt_pk_bf16_f32 v11, v18, v8
	v_cvt_pk_bf16_f32 v13, v19, v9
	v_lshlrev_b32_e32 v21, 16, v13
	v_lshlrev_b32_e32 v20, 16, v11
	v_pk_add_f32 v[20:21], v[18:19], v[20:21] neg_lo:[0,1] neg_hi:[0,1]
	s_nop 0
	v_cndmask_b32_e64 v21, v19, v21, s[8:9]
	v_cndmask_b32_e64 v20, v18, v20, s[8:9]
	v_and_b32_e32 v19, 0xffff0000, v13
	v_and_b32_e32 v18, 0xffff0000, v11
	v_pk_add_f32 v[18:19], v[8:9], v[18:19] neg_lo:[0,1] neg_hi:[0,1]
	s_nop 0
	v_cndmask_b32_e64 v31, v9, v19, s[8:9]
	v_cndmask_b32_e64 v36, v8, v18, s[8:9]
	v_pk_mul_f32 v[8:9], v[32:33], v[10:11] op_sel_hi:[1,0]
	v_pk_mul_f32 v[18:19], v[32:33], v[12:13] op_sel_hi:[1,0]
	v_pk_fma_f32 v[8:9], v[14:15], v[12:13], v[8:9] op_sel_hi:[1,0,1]
	v_pk_fma_f32 v[14:15], v[14:15], v[10:11], v[18:19] op_sel_hi:[1,0,1] neg_lo:[0,0,1] neg_hi:[0,0,1]
	s_nop 0
	v_cvt_pk_bf16_f32 v11, v14, v8
	v_cvt_pk_bf16_f32 v13, v15, v9
	v_lshlrev_b32_e32 v19, 16, v13
	v_lshlrev_b32_e32 v18, 16, v11
	v_pk_add_f32 v[18:19], v[14:15], v[18:19] neg_lo:[0,1] neg_hi:[0,1]
	s_nop 0
	v_cndmask_b32_e64 v19, v15, v19, s[8:9]
	v_cndmask_b32_e64 v18, v14, v18, s[8:9]
	v_and_b32_e32 v15, 0xffff0000, v13
	v_and_b32_e32 v14, 0xffff0000, v11
	v_pk_add_f32 v[14:15], v[8:9], v[14:15] neg_lo:[0,1] neg_hi:[0,1]
	s_nop 0
	v_cndmask_b32_e64 v15, v9, v15, s[8:9]
	v_cndmask_b32_e64 v14, v8, v14, s[8:9]
	v_pk_mul_f32 v[8:9], v[10:11], v[34:35] op_sel_hi:[0,1]
	v_pk_fma_f32 v[8:9], v[12:13], v[16:17], v[8:9] op_sel_hi:[0,1,1]
	v_pk_mul_f32 v[12:13], v[12:13], v[34:35] op_sel_hi:[0,1]
	v_pk_fma_f32 v[10:11], v[10:11], v[16:17], v[12:13] op_sel_hi:[0,1,1] neg_lo:[0,0,1] neg_hi:[0,0,1]
	v_cvt_pk_bf16_f32 v16, v10, v8
	v_cvt_pk_bf16_f32 v17, v11, v9
	v_lshlrev_b32_e32 v13, 16, v17
	v_lshlrev_b32_e32 v12, 16, v16
	v_pk_add_f32 v[12:13], v[10:11], v[12:13] neg_lo:[0,1] neg_hi:[0,1]
	v_cvt_pk_bf16_f32 v14, v14, v15
	v_cndmask_b32_e64 v13, v11, v13, s[8:9]
	v_cndmask_b32_e64 v12, v10, v12, s[8:9]
	v_and_b32_e32 v11, 0xffff0000, v17
	v_and_b32_e32 v10, 0xffff0000, v16
	v_pk_add_f32 v[10:11], v[8:9], v[10:11] neg_lo:[0,1] neg_hi:[0,1]
	s_nop 0
	v_cndmask_b32_e64 v17, v8, v10, s[8:9]
	v_cvt_pk_bf16_f32 v10, v18, v19
	global_load_dword v18, v[28:29], off offset:128
	global_load_dword v19, v[24:25], off offset:128
	v_cndmask_b32_e64 v16, v9, v11, s[8:9]
	v_cvt_pk_bf16_f32 v9, v20, v21
	v_cvt_pk_bf16_f32 v11, v12, v13
	v_cvt_pk_bf16_f32 v12, v27, v26
	v_cvt_pk_bf16_f32 v8, v22, v23
	v_cvt_pk_bf16_f32 v13, v36, v31
	v_cvt_pk_bf16_f32 v15, v17, v16
	v_mov_b32_e32 v17, s15
	v_or_b32_e32 v16, s18, v64
	v_lshlrev_b64 v[16:17], 6, v[16:17]
	v_lshl_add_u64 v[36:37], v[50:51], 0, v[16:17]
	s_waitcnt vmcnt(0)
	v_mul_f32_e32 v20, v30, v19
	v_mul_f32_e32 v21, 0.15915494, v20
	v_rndne_f32_e32 v21, v21
	v_fmac_f32_e32 v20, 0xc0c90fdb, v21
	v_fmac_f32_e32 v20, 0x343bbd2e, v21
	v_mul_f32_e32 v20, 0.15915494, v20
	v_sin_f32_e32 v21, v20
	v_cos_f32_e32 v26, v20
	v_mul_f32_e32 v20, v30, v18
	v_mul_f32_e32 v22, 0x3fb8aa3b, v20
	v_fma_f32 v23, v20, s92, -v22
	v_rndne_f32_e32 v27, v22
	v_fmac_f32_e32 v23, 0x32a5705f, v20
	v_sub_f32_e32 v22, v22, v27
	v_add_f32_e32 v22, v22, v23
	v_exp_f32_e32 v22, v22
	v_cvt_i32_f32_e32 v23, v27
	v_cmp_ngt_f32_e32 vcc, s65, v20
	v_ldexp_f32 v22, v22, v23
	s_nop 0
	v_cndmask_b32_e32 v22, 0, v22, vcc
	v_cmp_nlt_f32_e32 vcc, s56, v20
	s_nop 1
	v_cndmask_b32_e32 v27, v246, v22, vcc
	v_pk_mul_f32 v[22:23], v[18:19], v[18:19]
	v_mul_f32_e32 v20, v27, v21
	v_add_f32_e32 v21, v22, v23
	v_rcp_f32_e32 v31, v21
	v_fma_f32 v21, v27, v26, -1.0
	v_mov_b32_e32 v22, v19
	v_mov_b32_e32 v23, v18
	v_pk_mul_f32 v[22:23], v[22:23], v[20:21]
	v_pk_mul_f32 v[18:19], v[18:19], v[20:21]
	v_add_f32_e32 v22, v22, v23
	v_sub_f32_e32 v18, v18, v19
	v_lshl_add_u64 v[20:21], v[48:49], 0, v[16:17]
	v_mul_f32_e32 v26, v31, v22
	v_mul_f32_e32 v78, v31, v18
	global_load_dwordx4 v[16:19], v[20:21], off offset:16
	s_nop 0
	global_load_dwordx4 v[20:23], v[20:21], off
	s_nop 0
	global_load_dwordx4 v[32:35], v[36:37], off offset:16
	s_nop 0
	global_load_dwordx4 v[36:39], v[36:37], off
	s_nop 0
	global_load_dword v28, v[28:29], off offset:192
	s_nop 0
	global_load_dword v29, v[24:25], off offset:192
	s_waitcnt vmcnt(2)
	v_pk_mul_f32 v[80:81], v[36:37], v[26:27] op_sel_hi:[1,0]
	v_pk_mul_f32 v[36:37], v[36:37], v[78:79] op_sel_hi:[1,0]
	v_pk_fma_f32 v[80:81], v[20:21], v[78:79], v[80:81] op_sel_hi:[1,0,1]
	v_pk_fma_f32 v[20:21], v[20:21], v[26:27], v[36:37] op_sel_hi:[1,0,1] neg_lo:[0,0,1] neg_hi:[0,0,1]
	s_waitcnt vmcnt(0)
	v_mul_f32_e32 v24, v30, v29
	v_cvt_pk_bf16_f32 v27, v20, v80
	v_cvt_pk_bf16_f32 v31, v21, v81
	v_lshlrev_b32_e32 v37, 16, v31
	v_lshlrev_b32_e32 v36, 16, v27
	v_pk_add_f32 v[36:37], v[20:21], v[36:37] neg_lo:[0,1] neg_hi:[0,1]
	v_mul_f32_e32 v25, 0.15915494, v24
	v_cndmask_b32_e64 v43, v21, v37, s[8:9]
	v_cndmask_b32_e64 v73, v20, v36, s[8:9]
	v_and_b32_e32 v21, 0xffff0000, v31
	v_and_b32_e32 v20, 0xffff0000, v27
	v_pk_add_f32 v[20:21], v[80:81], v[20:21] neg_lo:[0,1] neg_hi:[0,1]
	v_pk_mul_f32 v[36:37], v[38:39], v[78:79] op_sel_hi:[1,0]
	v_cndmask_b32_e64 v27, v81, v21, s[8:9]
	v_cndmask_b32_e64 v31, v80, v20, s[8:9]
	v_pk_mul_f32 v[20:21], v[38:39], v[26:27] op_sel_hi:[1,0]
	v_rndne_f32_e32 v25, v25
	v_pk_fma_f32 v[20:21], v[22:23], v[78:79], v[20:21] op_sel_hi:[1,0,1]
	v_pk_fma_f32 v[22:23], v[22:23], v[26:27], v[36:37] op_sel_hi:[1,0,1] neg_lo:[0,0,1] neg_hi:[0,0,1]
	v_fmac_f32_e32 v24, 0xc0c90fdb, v25
	v_cvt_pk_bf16_f32 v38, v22, v20
	v_cvt_pk_bf16_f32 v39, v23, v21
	v_lshlrev_b32_e32 v37, 16, v39
	v_lshlrev_b32_e32 v36, 16, v38
	v_pk_add_f32 v[36:37], v[22:23], v[36:37] neg_lo:[0,1] neg_hi:[0,1]
	v_fmac_f32_e32 v24, 0x343bbd2e, v25
	v_cndmask_b32_e64 v37, v23, v37, s[8:9]
	v_cndmask_b32_e64 v36, v22, v36, s[8:9]
	v_and_b32_e32 v23, 0xffff0000, v39
	v_and_b32_e32 v22, 0xffff0000, v38
	v_pk_add_f32 v[22:23], v[20:21], v[22:23] neg_lo:[0,1] neg_hi:[0,1]
	v_mul_f32_e32 v24, 0.15915494, v24
	v_cndmask_b32_e64 v38, v21, v23, s[8:9]
	v_cndmask_b32_e64 v39, v20, v22, s[8:9]
	v_pk_mul_f32 v[20:21], v[32:33], v[26:27] op_sel_hi:[1,0]
	v_pk_mul_f32 v[22:23], v[32:33], v[78:79] op_sel_hi:[1,0]
	v_pk_fma_f32 v[20:21], v[16:17], v[78:79], v[20:21] op_sel_hi:[1,0,1]
	v_pk_fma_f32 v[16:17], v[16:17], v[26:27], v[22:23] op_sel_hi:[1,0,1] neg_lo:[0,0,1] neg_hi:[0,0,1]
	v_sin_f32_e32 v25, v24
	v_cvt_pk_bf16_f32 v32, v16, v20
	v_cvt_pk_bf16_f32 v33, v17, v21
	v_lshlrev_b32_e32 v23, 16, v33
	v_lshlrev_b32_e32 v22, 16, v32
	v_pk_add_f32 v[22:23], v[16:17], v[22:23] neg_lo:[0,1] neg_hi:[0,1]
	s_nop 0
	v_cndmask_b32_e64 v23, v17, v23, s[8:9]
	v_cndmask_b32_e64 v22, v16, v22, s[8:9]
	v_and_b32_e32 v17, 0xffff0000, v33
	v_and_b32_e32 v16, 0xffff0000, v32
	v_pk_add_f32 v[16:17], v[20:21], v[16:17] neg_lo:[0,1] neg_hi:[0,1]
	s_nop 0
	v_cndmask_b32_e64 v32, v21, v17, s[8:9]
	v_cndmask_b32_e64 v33, v20, v16, s[8:9]
	v_pk_mul_f32 v[16:17], v[26:27], v[34:35] op_sel_hi:[0,1]
	v_pk_mul_f32 v[20:21], v[78:79], v[34:35] op_sel_hi:[0,1]
	v_pk_fma_f32 v[16:17], v[78:79], v[18:19], v[16:17] op_sel_hi:[0,1,1]
	v_pk_fma_f32 v[18:19], v[26:27], v[18:19], v[20:21] op_sel_hi:[0,1,1] neg_lo:[0,0,1] neg_hi:[0,0,1]
	v_cvt_pk_bf16_f32 v26, v18, v16
	v_cvt_pk_bf16_f32 v34, v19, v17
	v_lshlrev_b32_e32 v21, 16, v34
	v_lshlrev_b32_e32 v20, 16, v26
	v_pk_add_f32 v[20:21], v[18:19], v[20:21] neg_lo:[0,1] neg_hi:[0,1]
	s_nop 0
	v_cndmask_b32_e64 v21, v19, v21, s[8:9]
	v_cndmask_b32_e64 v20, v18, v20, s[8:9]
	v_and_b32_e32 v19, 0xffff0000, v34
	v_and_b32_e32 v18, 0xffff0000, v26
	v_pk_add_f32 v[18:19], v[16:17], v[18:19] neg_lo:[0,1] neg_hi:[0,1]
	s_nop 0
	v_cndmask_b32_e64 v34, v16, v18, s[8:9]
	v_cvt_pk_bf16_f32 v18, v22, v23
	v_cvt_pk_bf16_f32 v22, v33, v32
	v_cos_f32_e32 v32, v24
	v_mul_f32_e32 v24, v30, v28
	v_mul_f32_e32 v30, 0x3fb8aa3b, v24
	v_cndmask_b32_e64 v26, v17, v19, s[8:9]
	v_cvt_pk_bf16_f32 v19, v20, v21
	v_cvt_pk_bf16_f32 v20, v31, v27
	v_fma_f32 v31, v24, s92, -v30
	v_rndne_f32_e32 v33, v30
	v_fmac_f32_e32 v31, 0x32a5705f, v24
	v_sub_f32_e32 v30, v30, v33
	v_add_f32_e32 v30, v30, v31
	v_exp_f32_e32 v30, v30
	v_cvt_i32_f32_e32 v31, v33
	v_cmp_ngt_f32_e32 vcc, s65, v24
	v_cvt_pk_bf16_f32 v23, v34, v26
	v_mov_b32_e32 v27, s15
	v_ldexp_f32 v30, v30, v31
	v_cndmask_b32_e32 v30, 0, v30, vcc
	v_cmp_nlt_f32_e32 vcc, s56, v24
	v_or_b32_e32 v26, s18, v66
	v_cvt_pk_bf16_f32 v17, v36, v37
	v_cndmask_b32_e32 v33, v246, v30, vcc
	v_pk_mul_f32 v[30:31], v[28:29], v[28:29]
	v_mul_f32_e32 v24, v33, v25
	v_add_f32_e32 v25, v30, v31
	v_rcp_f32_e32 v34, v25
	v_fma_f32 v25, v33, v32, -1.0
	v_mov_b32_e32 v30, v29
	v_mov_b32_e32 v31, v28
	v_pk_mul_f32 v[30:31], v[30:31], v[24:25]
	v_pk_mul_f32 v[24:25], v[28:29], v[24:25]
	v_add_f32_e32 v30, v30, v31
	v_sub_f32_e32 v24, v24, v25
	v_mul_f32_e32 v80, v34, v24
	v_lshlrev_b64 v[24:25], 6, v[26:27]
	v_lshl_add_u64 v[28:29], v[48:49], 0, v[24:25]
	v_lshl_add_u64 v[36:37], v[50:51], 0, v[24:25]
	v_cvt_pk_bf16_f32 v21, v39, v38
	v_mul_f32_e32 v78, v34, v30
	global_load_dwordx4 v[24:27], v[28:29], off offset:16
	global_load_dwordx4 v[32:35], v[28:29], off
	s_nop 0
	global_load_dwordx4 v[28:31], v[36:37], off offset:16
	s_nop 0
	global_load_dwordx4 v[36:39], v[36:37], off
	v_cvt_pk_bf16_f32 v16, v73, v43
	s_mov_b64 s[18:19], 0
	s_waitcnt vmcnt(0)
	v_pk_mul_f32 v[82:83], v[36:37], v[78:79] op_sel_hi:[1,0]
	v_pk_mul_f32 v[36:37], v[36:37], v[80:81] op_sel_hi:[1,0]
	v_pk_fma_f32 v[82:83], v[32:33], v[80:81], v[82:83] op_sel_hi:[1,0,1]
	v_pk_fma_f32 v[32:33], v[32:33], v[78:79], v[36:37] op_sel_hi:[1,0,1] neg_lo:[0,0,1] neg_hi:[0,0,1]
	s_nop 0
	v_cvt_pk_bf16_f32 v43, v32, v82
	v_cvt_pk_bf16_f32 v73, v33, v83
	v_lshlrev_b32_e32 v37, 16, v73
	v_lshlrev_b32_e32 v36, 16, v43
	v_pk_add_f32 v[36:37], v[32:33], v[36:37] neg_lo:[0,1] neg_hi:[0,1]
	s_nop 0
	v_cndmask_b32_e64 v75, v33, v37, s[8:9]
	v_cndmask_b32_e64 v77, v32, v36, s[8:9]
	v_and_b32_e32 v33, 0xffff0000, v73
	v_and_b32_e32 v32, 0xffff0000, v43
	v_pk_add_f32 v[32:33], v[82:83], v[32:33] neg_lo:[0,1] neg_hi:[0,1]
	v_pk_mul_f32 v[36:37], v[38:39], v[80:81] op_sel_hi:[1,0]
	v_cndmask_b32_e64 v43, v83, v33, s[8:9]
	v_cndmask_b32_e64 v73, v82, v32, s[8:9]
	v_pk_mul_f32 v[32:33], v[38:39], v[78:79] op_sel_hi:[1,0]
	v_pk_mul_f32 v[92:93], v[42:43], v[40:41] op_sel_hi:[0,1]
	v_pk_fma_f32 v[32:33], v[34:35], v[80:81], v[32:33] op_sel_hi:[1,0,1]
	v_pk_fma_f32 v[34:35], v[34:35], v[78:79], v[36:37] op_sel_hi:[1,0,1] neg_lo:[0,0,1] neg_hi:[0,0,1]
	v_mov_b32_e32 v82, v93
	v_cvt_pk_bf16_f32 v38, v34, v32
	v_cvt_pk_bf16_f32 v39, v35, v33
	v_lshlrev_b32_e32 v37, 16, v39
	v_lshlrev_b32_e32 v36, 16, v38
	v_pk_add_f32 v[36:37], v[34:35], v[36:37] neg_lo:[0,1] neg_hi:[0,1]
	v_mov_b32_e32 v83, v93
	v_cndmask_b32_e64 v37, v35, v37, s[8:9]
	v_cndmask_b32_e64 v36, v34, v36, s[8:9]
	v_and_b32_e32 v35, 0xffff0000, v39
	v_and_b32_e32 v34, 0xffff0000, v38
	v_pk_add_f32 v[34:35], v[32:33], v[34:35] neg_lo:[0,1] neg_hi:[0,1]
	s_nop 0
	v_cndmask_b32_e64 v35, v33, v35, s[8:9]
	v_cndmask_b32_e64 v34, v32, v34, s[8:9]
	v_pk_mul_f32 v[32:33], v[28:29], v[78:79] op_sel_hi:[1,0]
	v_pk_mul_f32 v[28:29], v[28:29], v[80:81] op_sel_hi:[1,0]
	v_pk_fma_f32 v[32:33], v[24:25], v[80:81], v[32:33] op_sel_hi:[1,0,1]
	v_pk_fma_f32 v[24:25], v[24:25], v[78:79], v[28:29] op_sel_hi:[1,0,1] neg_lo:[0,0,1] neg_hi:[0,0,1]
	s_nop 0
	v_cvt_pk_bf16_f32 v38, v24, v32
	v_cvt_pk_bf16_f32 v39, v25, v33
	v_lshlrev_b32_e32 v29, 16, v39
	v_lshlrev_b32_e32 v28, 16, v38
	v_pk_add_f32 v[28:29], v[24:25], v[28:29] neg_lo:[0,1] neg_hi:[0,1]
	s_nop 0
	v_cndmask_b32_e64 v79, v25, v29, s[8:9]
	v_cndmask_b32_e64 v81, v24, v28, s[8:9]
	v_and_b32_e32 v25, 0xffff0000, v39
	v_and_b32_e32 v24, 0xffff0000, v38
	v_pk_add_f32 v[24:25], v[32:33], v[24:25] neg_lo:[0,1] neg_hi:[0,1]
	v_pk_mul_f32 v[28:29], v[80:81], v[30:31] op_sel_hi:[0,1]
	v_cndmask_b32_e64 v33, v33, v25, s[8:9]
	v_cndmask_b32_e64 v32, v32, v24, s[8:9]
	v_pk_mul_f32 v[24:25], v[78:79], v[30:31] op_sel_hi:[0,1]
	v_pk_fma_f32 v[24:25], v[80:81], v[26:27], v[24:25] op_sel_hi:[0,1,1]
	v_pk_fma_f32 v[26:27], v[78:79], v[26:27], v[28:29] op_sel_hi:[0,1,1] neg_lo:[0,0,1] neg_hi:[0,0,1]
	v_cvt_pk_bf16_f32 v30, v26, v24
	v_cvt_pk_bf16_f32 v31, v27, v25
	v_lshlrev_b32_e32 v29, 16, v31
	v_lshlrev_b32_e32 v28, 16, v30
	v_pk_add_f32 v[28:29], v[26:27], v[28:29] neg_lo:[0,1] neg_hi:[0,1]
	v_mov_b32_e32 v80, v92
	v_cndmask_b32_e64 v29, v27, v29, s[8:9]
	v_cndmask_b32_e64 v28, v26, v28, s[8:9]
	v_and_b32_e32 v27, 0xffff0000, v31
	v_and_b32_e32 v26, 0xffff0000, v30
	v_pk_add_f32 v[26:27], v[24:25], v[26:27] neg_lo:[0,1] neg_hi:[0,1]
	v_cvt_pk_bf16_f32 v30, v32, v33
	v_lshl_add_u64 v[32:33], v[52:53], 0, s[0:1]
	v_cndmask_b32_e64 v31, v25, v27, s[8:9]
	v_cvt_pk_bf16_f32 v27, v28, v29
	v_cvt_pk_bf16_f32 v29, v34, v35
	v_lshl_add_u64 v[34:35], v[54:55], 0, s[0:1]
	global_load_dword v98, v[32:33], off
	global_load_dword v114, v[34:35], off
	global_load_dword v99, v[32:33], off offset:16
	global_load_dword v115, v[34:35], off offset:16
	global_load_dword v100, v[32:33], off offset:32
	global_load_dword v116, v[34:35], off offset:32
	global_load_dword v101, v[32:33], off offset:48
	global_load_dword v117, v[34:35], off offset:48
	global_load_dword v102, v[32:33], off offset:64
	global_load_dword v118, v[34:35], off offset:64
	global_load_dword v103, v[32:33], off offset:80
	global_load_dword v119, v[34:35], off offset:80
	global_load_dword v104, v[32:33], off offset:96
	global_load_dword v120, v[34:35], off offset:96
	global_load_dword v105, v[32:33], off offset:112
	global_load_dword v121, v[34:35], off offset:112
	global_load_dword v106, v[32:33], off offset:128
	global_load_dword v122, v[34:35], off offset:128
	global_load_dword v107, v[32:33], off offset:144
	global_load_dword v123, v[34:35], off offset:144
	global_load_dword v108, v[32:33], off offset:160
	global_load_dword v124, v[34:35], off offset:160
	global_load_dword v109, v[32:33], off offset:176
	global_load_dword v125, v[34:35], off offset:176
	global_load_dword v110, v[32:33], off offset:192
	global_load_dword v126, v[34:35], off offset:192
	global_load_dword v111, v[32:33], off offset:208
	global_load_dword v127, v[34:35], off offset:208
	global_load_dword v112, v[32:33], off offset:224
	global_load_dword v128, v[34:35], off offset:224
	global_load_dword v113, v[32:33], off offset:240
	global_load_dword v129, v[34:35], off offset:240
	s_ashr_i32 s0, s21, 5
	s_ashr_i32 s1, s0, 31
	s_lshl_b64 s[0:1], s[0:1], 11
	v_cndmask_b32_e64 v38, v24, v26, s[8:9]
	v_cvt_pk_bf16_f32 v26, v81, v79
	v_lshl_add_u64 v[78:79], s[0:1], 0, v[58:59]
	v_cvt_pk_bf16_f32 v31, v38, v31
	v_or_b32_e32 v40, v78, v46
	v_mov_b64_e32 v[38:39], s[70:71]
	v_mad_u64_u32 v[38:39], s[0:1], v40, s97, v[38:39]
	v_cvt_pk_bf16_f32 v25, v36, v37
	v_lshl_add_u64 v[32:33], v[56:57], 0, s[52:53]
	v_mad_u64_u32 v[36:37], s[0:1], v40, s97, 0
	v_mad_i32_i24 v39, v79, s97, v39
	s_lshl_b32 s52, s20, 5
	v_lshl_add_u64 v[38:39], v[38:39], 0, s[52:53]
	s_mov_b64 s[0:1], 0x12141400
	v_cvt_pk_bf16_f32 v28, v73, v43
	v_lshl_add_u64 v[88:89], v[38:39], 0, s[0:1]
	v_mov_b32_e32 v73, v199
	v_lshl_add_u64 v[90:91], v[88:89], 0, v[72:73]
	global_load_dwordx4 v[40:43], v[90:91], off
	v_mad_i32_i24 v87, v79, s97, v37
	global_load_dwordx4 v[32:35], v[32:33], off
	v_or_b32_e32 v86, s52, v36
	v_cvt_pk_bf16_f32 v24, v77, v75
	v_mov_b32_e32 v81, v92
	v_lshl_add_u64 v[84:85], v[68:69], 0, v[86:87]
	v_mov_b32_e32 v77, v76
	s_waitcnt vmcnt(1)
	v_mov_b64_e32 v[36:37], v[40:41]
	v_mov_b64_e32 v[38:39], v[42:43]
	v_mov_b64_e32 v[228:229], v[84:85]
	s_mov_b64 s[24:25], 0x28000
	v_lshl_add_u64 v[228:229], v[228:229], 0, s[24:25]
	global_load_dword v212, v[228:229], off
	v_lshl_add_u64 v[228:229], v[228:229], 0, s[24:25]
	global_load_dword v213, v[228:229], off
	v_lshl_add_u64 v[228:229], v[228:229], 0, s[24:25]
	global_load_dword v214, v[228:229], off
	v_lshl_add_u64 v[228:229], v[228:229], 0, s[24:25]
	global_load_dword v215, v[228:229], off
	v_lshl_add_u64 v[228:229], v[228:229], 0, s[24:25]
	global_load_dword v216, v[228:229], off
	v_lshl_add_u64 v[228:229], v[228:229], 0, s[24:25]
	global_load_dword v217, v[228:229], off
	v_lshl_add_u64 v[228:229], v[228:229], 0, s[24:25]
	global_load_dword v218, v[228:229], off
	v_lshl_add_u64 v[228:229], v[228:229], 0, s[24:25]
	global_load_dword v219, v[228:229], off
	v_lshl_add_u64 v[228:229], v[228:229], 0, s[24:25]
	global_load_dword v220, v[228:229], off
	v_lshl_add_u64 v[228:229], v[228:229], 0, s[24:25]
	global_load_dword v221, v[228:229], off
	v_lshl_add_u64 v[228:229], v[228:229], 0, s[24:25]
	global_load_dword v222, v[228:229], off
	v_lshl_add_u64 v[228:229], v[228:229], 0, s[24:25]
	global_load_dword v223, v[228:229], off
	v_lshl_add_u64 v[228:229], v[228:229], 0, s[24:25]
	global_load_dword v224, v[228:229], off
	v_lshl_add_u64 v[228:229], v[228:229], 0, s[24:25]
	global_load_dword v225, v[228:229], off
	s_branch .LBB0_284
